# v101 plus the same tail-bookkeeping move in the diff attention loop (behind the last QK MFMA)
# baseline (speedup 1.0000x reference)
.Latt_diff_dmaend:
	s_waitcnt lgkmcnt(2)
	v_mfma_f32_32x32x16_bf16 v[64:79], v[112:115], v[130:133], v[96:111]
	ds_read_b128 v[112:115], v242 offset:4608
	v_mfma_f32_32x32x16_bf16 v[64:79], v[116:119], v[134:137], v[64:79]
	ds_read_b128 v[116:119], v242 offset:4640
	s_waitcnt lgkmcnt(2)
	v_mfma_f32_32x32x16_bf16 v[64:79], v[120:123], v[138:141], v[64:79]
	ds_read_b128 v[120:123], v242 offset:4672
	v_mfma_f32_32x32x16_bf16 v[64:79], v[124:127], v[142:145], v[64:79]
	ds_read_b128 v[124:127], v242 offset:4704
	s_waitcnt lgkmcnt(2)
	v_mfma_f32_32x32x16_bf16 v[80:95], v[112:115], v[130:133], v[96:111]
	v_mfma_f32_32x32x16_bf16 v[80:95], v[116:119], v[134:137], v[80:95]
	s_waitcnt lgkmcnt(0)
	v_mfma_f32_32x32x16_bf16 v[80:95], v[120:123], v[138:141], v[80:95]
	v_mfma_f32_32x32x16_bf16 v[80:95], v[124:127], v[142:145], v[80:95]
	ds_read_b128 v[112:115], v243 offset:27648
	ds_read_b128 v[116:119], v243 offset:32256
	ds_read_b128 v[120:123], v243 offset:36864
	ds_read_b128 v[124:127], v243 offset:41472
	s_add_i32 s30, s50, 1
	s_cmp_lg_u32 s50, 2
	s_cselect_b32 s98, s30, 0
	s_add_i32 s43, s43, 64
	s_add_i32 s45, s45, 64
	s_mov_b32 s53, s51
	s_mov_b32 s51, s50
	s_mov_b32 s50, s98
	v_max3_f32 v227, v64, v65, v66
	v_max3_f32 v228, v67, v68, v69
	v_max3_f32 v227, v227, v70, v71
	v_max3_f32 v228, v228, v72, v73
	v_max3_f32 v227, v227, v74, v75
	v_max3_f32 v228, v228, v76, v77
	v_max3_f32 v227, v227, v78, v79
	v_max3_f32 v229, v80, v81, v82
	v_max3_f32 v226, v83, v84, v85
	v_max3_f32 v229, v229, v86, v87
	v_max3_f32 v226, v226, v88, v89
	v_max3_f32 v229, v229, v90, v91
	v_max3_f32 v226, v226, v92, v93
	v_max3_f32 v229, v229, v94, v95
	v_max3_f32 v226, v226, v227, v228
	v_max_f32_e32 v226, v226, v229
	v_cmp_lt_f32_e32 vcc, s58, v226
	s_cbranch_vccnz .Latt_diff_rare

.Latt_diff_wd:
	s_add_i32 s52, s52, 1
	s_mul_i32 s30, s53, 0x2400
	v_add_u32_e32 v242, s30, v173
	s_mul_i32 s30, s53, 0x4800
	v_add_u32_e32 v243, s30, v174
	s_cmp_eq_u32 s21, s52
	s_barrier
	s_cbranch_scc0 .LBB0_107
	s_branch .LBB0_88
